# phase-2 indexer item table re-balanced (same entries, same XCD grouping) under cost model 0.55*nj+0.67*NS(nj)+8 per entry
# speedup vs baseline: 1.0122x; 1.0122x over previous
_ZL7idx_tab:
	.short	152
	.short	214
	.short	212
	.short	131
	.short	65535
	.short	344
	.short	278
	.short	340
	.short	259
	.short	65535
	.short	600
	.short	726
	.short	660
	.short	643
	.short	65535
	.short	792
	.short	918
	.short	916
	.short	899
	.short	65535
	.short	1112
	.short	1046
	.short	1236
	.short	1218
	.short	65535
	.short	1368
	.short	1366
	.short	1300
	.short	1346
	.short	65535
	.short	1624
	.short	1750
	.short	1748
	.short	1730
	.short	65535
	.short	1816
	.short	1878
	.short	2004
	.short	1986
	.short	65535
	.short	88
	.short	22
	.short	20
	.short	3
	.short	65535
	.short	280
	.short	406
	.short	468
	.short	451
	.short	65535
	.short	664
	.short	662
	.short	724
	.short	577
	.short	65535
	.short	920
	.short	982
	.short	980
	.short	963
	.short	65535
	.short	1048
	.short	1174
	.short	1044
	.short	1219
	.short	65535
	.short	1432
	.short	1430
	.short	1364
	.short	1411
	.short	65535
	.short	1688
	.short	1558
	.short	1556
	.short	1537
	.short	65535
	.short	1880
	.short	1942
	.short	1876
	.short	1795
	.short	65535
	.short	32
	.short	142
	.short	11
	.short	71
	.short	193
	.short	224
	.short	398
	.short	459
	.short	263
	.short	387
	.short	352
	.short	526
	.short	523
	.short	519
	.short	513
	.short	416
	.short	846
	.short	779
	.short	775
	.short	834
	.short	608
	.short	1038
	.short	1035
	.short	1223
	.short	1153
	.short	672
	.short	1358
	.short	1355
	.short	1479
	.short	1344
	.short	800
	.short	1678
	.short	1547
	.short	1671
	.short	1667
	.short	928
	.short	1934
	.short	1931
	.short	1863
	.short	1857
	.short	96
	.short	78
	.short	76
	.short	6
	.short	129
	.short	160
	.short	334
	.short	396
	.short	390
	.short	320
	.short	288
	.short	590
	.short	524
	.short	646
	.short	640
	.short	480
	.short	974
	.short	908
	.short	774
	.short	832
	.short	544
	.short	1230
	.short	1164
	.short	1030
	.short	1216
	.short	736
	.short	1294
	.short	1420
	.short	1350
	.short	1473
	.short	864
	.short	1550
	.short	1740
	.short	1606
	.short	1601
	.short	992
	.short	1998
	.short	1996
	.short	1798
	.short	1984
	.short	24
	.short	81
	.short	202
	.short	132
	.short	65535
	.short	472
	.short	401
	.short	458
	.short	324
	.short	65535
	.short	536
	.short	721
	.short	650
	.short	708
	.short	65535
	.short	984
	.short	977
	.short	778
	.short	836
	.short	65535
	.short	1176
	.short	1041
	.short	1162
	.short	1028
	.short	65535
	.short	1304
	.short	1425
	.short	1290
	.short	1284
	.short	65535
	.short	1560
	.short	1745
	.short	1674
	.short	1604
	.short	65535
	.short	1944
	.short	1937
	.short	1866
	.short	1988
	.short	65535
	.short	216
	.short	145
	.short	138
	.short	4
	.short	65535
	.short	408
	.short	273
	.short	330
	.short	260
	.short	65535
	.short	728
	.short	593
	.short	714
	.short	516
	.short	65535
	.short	856
	.short	785
	.short	842
	.short	964
	.short	65535
	.short	1240
	.short	1233
	.short	1034
	.short	1220
	.short	65535
	.short	1496
	.short	1361
	.short	1482
	.short	1412
	.short	65535
	.short	1752
	.short	1617
	.short	1738
	.short	1732
	.short	65535
	.short	2008
	.short	2001
	.short	1994
	.short	1860
	.short	65535
	.short	95
	.short	13
	.short	12
	.short	199
	.short	67
	.short	287
	.short	397
	.short	332
	.short	327
	.short	384
	.short	735
	.short	653
	.short	716
	.short	583
	.short	515
	.short	799
	.short	973
	.short	844
	.short	903
	.short	896
	.short	1247
	.short	1101
	.short	1036
	.short	1159
	.short	1088
	.short	1503
	.short	1421
	.short	1356
	.short	1351
	.short	1474
	.short	1695
	.short	1549
	.short	1676
	.short	1607
	.short	1664
	.short	2015
	.short	1805
	.short	1868
	.short	1927
	.short	1859
	.short	159
	.short	141
	.short	75
	.short	134
	.short	0
	.short	415
	.short	333
	.short	267
	.short	262
	.short	322
	.short	607
	.short	525
	.short	587
	.short	710
	.short	706
	.short	991
	.short	845
	.short	971
	.short	838
	.short	898
	.short	1055
	.short	1229
	.short	1163
	.short	1158
	.short	1090
	.short	1375
	.short	1293
	.short	1483
	.short	1414
	.short	1410
	.short	1759
	.short	1677
	.short	1611
	.short	1670
	.short	1666
	.short	1823
	.short	1997
	.short	1867
	.short	1926
	.short	1922
	.short	92
	.short	23
	.short	211
	.short	65535
	.short	65535
	.short	412
	.short	343
	.short	403
	.short	65535
	.short	65535
	.short	668
	.short	663
	.short	595
	.short	65535
	.short	65535
	.short	796
	.short	919
	.short	915
	.short	65535
	.short	65535
	.short	1052
	.short	1111
	.short	1171
	.short	65535
	.short	65535
	.short	1308
	.short	1367
	.short	1299
	.short	65535
	.short	65535
	.short	1628
	.short	1751
	.short	1555
	.short	65535
	.short	65535
	.short	1884
	.short	2007
	.short	1875
	.short	65535
	.short	65535
	.short	28
	.short	215
	.short	19
	.short	65535
	.short	65535
	.short	284
	.short	407
	.short	275
	.short	65535
	.short	65535
	.short	540
	.short	727
	.short	531
	.short	65535
	.short	65535
	.short	988
	.short	791
	.short	787
	.short	65535
	.short	65535
	.short	1244
	.short	1047
	.short	1235
	.short	65535
	.short	65535
	.short	1500
	.short	1495
	.short	1491
	.short	65535
	.short	65535
	.short	1564
	.short	1687
	.short	1747
	.short	65535
	.short	65535
	.short	1948
	.short	1879
	.short	2003
	.short	65535
	.short	65535
	.short	158
	.short	149
	.short	147
	.short	65535
	.short	65535
	.short	414
	.short	277
	.short	339
	.short	65535
	.short	65535
	.short	670
	.short	597
	.short	723
	.short	65535
	.short	65535
	.short	990
	.short	917
	.short	979
	.short	65535
	.short	65535
	.short	1246
	.short	1237
	.short	1043
	.short	65535
	.short	65535
	.short	1438
	.short	1429
	.short	1427
	.short	65535
	.short	65535
	.short	1758
	.short	1557
	.short	1683
	.short	65535
	.short	65535
	.short	1822
	.short	1877
	.short	1811
	.short	65535
	.short	65535
	.short	222
	.short	213
	.short	83
	.short	65535
	.short	65535
	.short	478
	.short	341
	.short	467
	.short	65535
	.short	65535
	.short	542
	.short	533
	.short	659
	.short	65535
	.short	65535
	.short	926
	.short	981
	.short	851
	.short	65535
	.short	65535
	.short	1118
	.short	1109
	.short	1107
	.short	65535
	.short	65535
	.short	1502
	.short	1301
	.short	1363
	.short	65535
	.short	65535
	.short	1630
	.short	1749
	.short	1619
	.short	65535
	.short	65535
	.short	1886
	.short	1941
	.short	1939
	.short	65535
	.short	65535
	.short	93
	.short	151
	.short	210
	.short	65535
	.short	65535
	.short	477
	.short	471
	.short	466
	.short	65535
	.short	65535
	.short	541
	.short	599
	.short	658
	.short	65535
	.short	65535
	.short	925
	.short	855
	.short	850
	.short	65535
	.short	65535
	.short	1245
	.short	1175
	.short	1234
	.short	65535
	.short	65535
	.short	1309
	.short	1303
	.short	1426
	.short	65535
	.short	65535
	.short	1757
	.short	1559
	.short	1682
	.short	65535
	.short	65535
	.short	1885
	.short	1943
	.short	1810
	.short	65535
	.short	65535
	.short	29
	.short	87
	.short	82
	.short	65535
	.short	65535
	.short	413
	.short	279
	.short	402
	.short	65535
	.short	65535
	.short	733
	.short	535
	.short	722
	.short	65535
	.short	65535
	.short	797
	.short	983
	.short	914
	.short	65535
	.short	65535
	.short	1053
	.short	1239
	.short	1106
	.short	65535
	.short	65535
	.short	1437
	.short	1431
	.short	1362
	.short	65535
	.short	65535
	.short	1693
	.short	1623
	.short	1618
	.short	65535
	.short	65535
	.short	1821
	.short	1815
	.short	2002
	.short	65535
	.short	65535
	.short	220
	.short	218
	.short	206
	.short	195
	.short	128
	.short	476
	.short	346
	.short	462
	.short	258
	.short	257
	.short	732
	.short	602
	.short	718
	.short	707
	.short	576
	.short	860
	.short	858
	.short	782
	.short	771
	.short	960
	.short	1116
	.short	1178
	.short	1102
	.short	1155
	.short	1091
	.short	1436
	.short	1370
	.short	1422
	.short	1283
	.short	1280
	.short	1756
	.short	1754
	.short	1742
	.short	1731
	.short	1600
	.short	2012
	.short	1946
	.short	1870
	.short	1923
	.short	1792
	.short	91
	.short	219
	.short	14
	.short	2
	.short	192
	.short	347
	.short	411
	.short	270
	.short	323
	.short	385
	.short	667
	.short	603
	.short	654
	.short	578
	.short	579
	.short	795
	.short	987
	.short	910
	.short	835
	.short	833
	.short	1179
	.short	1051
	.short	1166
	.short	1026
	.short	1024
	.short	1499
	.short	1371
	.short	1486
	.short	1409
	.short	1408
	.short	1563
	.short	1627
	.short	1614
	.short	1538
	.short	1728
	.short	1819
	.short	2011
	.short	1806
	.short	1987
	.short	1920
	.short	30
	.short	207
	.short	204
	.short	70
	.short	130
	.short	350
	.short	463
	.short	268
	.short	326
	.short	450
	.short	734
	.short	591
	.short	652
	.short	518
	.short	705
	.short	862
	.short	783
	.short	972
	.short	966
	.short	962
	.short	1054
	.short	1039
	.short	1100
	.short	1222
	.short	1154
	.short	1310
	.short	1359
	.short	1292
	.short	1478
	.short	1472
	.short	1694
	.short	1743
	.short	1612
	.short	1734
	.short	1603
	.short	2014
	.short	1871
	.short	1804
	.short	1862
	.short	1794
	.short	94
	.short	79
	.short	140
	.short	198
	.short	194
	.short	286
	.short	335
	.short	460
	.short	454
	.short	448
	.short	606
	.short	655
	.short	588
	.short	582
	.short	641
	.short	798
	.short	847
	.short	780
	.short	902
	.short	897
	.short	1182
	.short	1167
	.short	1228
	.short	1094
	.short	1089
	.short	1374
	.short	1423
	.short	1484
	.short	1286
	.short	1281
	.short	1566
	.short	1679
	.short	1548
	.short	1542
	.short	1602
	.short	1950
	.short	1935
	.short	1932
	.short	1990
	.short	1921
	.short	90
	.short	86
	.short	85
	.short	66
	.short	1
	.short	410
	.short	470
	.short	469
	.short	256
	.short	449
	.short	730
	.short	598
	.short	725
	.short	642
	.short	514
	.short	922
	.short	854
	.short	853
	.short	769
	.short	961
	.short	1114
	.short	1238
	.short	1173
	.short	1027
	.short	1152
	.short	1306
	.short	1302
	.short	1365
	.short	1347
	.short	1345
	.short	1626
	.short	1686
	.short	1621
	.short	1536
	.short	1665
	.short	2010
	.short	2006
	.short	1813
	.short	1858
	.short	1856
	.short	156
	.short	150
	.short	21
	.short	65535
	.short	65535
	.short	348
	.short	342
	.short	405
	.short	65535
	.short	65535
	.short	604
	.short	534
	.short	661
	.short	65535
	.short	65535
	.short	924
	.short	790
	.short	789
	.short	65535
	.short	65535
	.short	1180
	.short	1110
	.short	1045
	.short	65535
	.short	65535
	.short	1372
	.short	1494
	.short	1493
	.short	65535
	.short	65535
	.short	1692
	.short	1622
	.short	1685
	.short	65535
	.short	65535
	.short	1820
	.short	1814
	.short	2005
	.short	65535
	.short	65535
	.short	84
	.short	146
	.short	10
	.short	200
	.short	65535
	.short	404
	.short	338
	.short	266
	.short	392
	.short	65535
	.short	596
	.short	530
	.short	522
	.short	520
	.short	65535
	.short	852
	.short	978
	.short	970
	.short	776
	.short	65535
	.short	1172
	.short	1042
	.short	1226
	.short	1160
	.short	65535
	.short	1428
	.short	1490
	.short	1354
	.short	1288
	.short	65535
	.short	1684
	.short	1746
	.short	1610
	.short	1608
	.short	65535
	.short	1812
	.short	1874
	.short	1930
	.short	1864
	.short	65535
	.short	148
	.short	18
	.short	74
	.short	136
	.short	65535
	.short	276
	.short	274
	.short	394
	.short	456
	.short	65535
	.short	532
	.short	594
	.short	586
	.short	584
	.short	65535
	.short	788
	.short	786
	.short	906
	.short	840
	.short	65535
	.short	1108
	.short	1170
	.short	1098
	.short	1032
	.short	65535
	.short	1492
	.short	1298
	.short	1418
	.short	1480
	.short	65535
	.short	1620
	.short	1554
	.short	1546
	.short	1736
	.short	65535
	.short	1940
	.short	1938
	.short	1802
	.short	1800
	.short	65535
	.short	25
	.short	17
	.short	72
	.short	133
	.short	65535
	.short	281
	.short	337
	.short	328
	.short	325
	.short	65535
	.short	665
	.short	529
	.short	712
	.short	709
	.short	65535
	.short	857
	.short	849
	.short	968
	.short	837
	.short	65535
	.short	1241
	.short	1169
	.short	1096
	.short	1157
	.short	65535
	.short	1305
	.short	1489
	.short	1352
	.short	1477
	.short	65535
	.short	1753
	.short	1553
	.short	1544
	.short	1541
	.short	65535
	.short	1945
	.short	1873
	.short	1928
	.short	1925
	.short	65535
	.short	89
	.short	209
	.short	8
	.short	197
	.short	65535
	.short	473
	.short	465
	.short	264
	.short	453
	.short	65535
	.short	729
	.short	657
	.short	648
	.short	581
	.short	65535
	.short	985
	.short	913
	.short	904
	.short	773
	.short	65535
	.short	1177
	.short	1105
	.short	1224
	.short	1093
	.short	65535
	.short	1433
	.short	1297
	.short	1416
	.short	1349
	.short	65535
	.short	1689
	.short	1681
	.short	1672
	.short	1605
	.short	65535
	.short	1817
	.short	1809
	.short	1992
	.short	1797
	.short	65535
	.short	157
	.short	143
	.short	77
	.short	7
	.short	64
	.short	285
	.short	399
	.short	269
	.short	391
	.short	386
	.short	669
	.short	527
	.short	589
	.short	647
	.short	512
	.short	861
	.short	911
	.short	781
	.short	967
	.short	768
	.short	1181
	.short	1103
	.short	1037
	.short	1031
	.short	1217
	.short	1373
	.short	1487
	.short	1357
	.short	1415
	.short	1475
	.short	1629
	.short	1615
	.short	1613
	.short	1735
	.short	1539
	.short	1949
	.short	1999
	.short	1869
	.short	1991
	.short	1793
	.short	221
	.short	15
	.short	205
	.short	135
	.short	65
	.short	349
	.short	271
	.short	461
	.short	455
	.short	321
	.short	605
	.short	719
	.short	717
	.short	711
	.short	704
	.short	989
	.short	975
	.short	909
	.short	839
	.short	770
	.short	1117
	.short	1231
	.short	1165
	.short	1095
	.short	1025
	.short	1501
	.short	1295
	.short	1485
	.short	1287
	.short	1282
	.short	1565
	.short	1551
	.short	1741
	.short	1543
	.short	1729
	.short	2013
	.short	1807
	.short	1933
	.short	1799
	.short	1985
	.short	217
	.short	80
	.short	201
	.short	69
	.short	65535
	.short	409
	.short	400
	.short	457
	.short	261
	.short	65535
	.short	537
	.short	656
	.short	585
	.short	517
	.short	65535
	.short	793
	.short	848
	.short	969
	.short	901
	.short	65535
	.short	1113
	.short	1040
	.short	1033
	.short	1029
	.short	65535
	.short	1369
	.short	1360
	.short	1289
	.short	1285
	.short	65535
	.short	1561
	.short	1616
	.short	1673
	.short	1669
	.short	65535
	.short	2009
	.short	1872
	.short	1865
	.short	1861
	.short	65535
	.short	153
	.short	208
	.short	9
	.short	5
	.short	65535
	.short	345
	.short	336
	.short	329
	.short	389
	.short	65535
	.short	601
	.short	592
	.short	521
	.short	645
	.short	65535
	.short	921
	.short	912
	.short	841
	.short	965
	.short	65535
	.short	1049
	.short	1168
	.short	1097
	.short	1221
	.short	65535
	.short	1497
	.short	1488
	.short	1481
	.short	1413
	.short	65535
	.short	1625
	.short	1552
	.short	1609
	.short	1733
	.short	65535
	.short	1881
	.short	1808
	.short	1929
	.short	1989
	.short	65535
	.short	31
	.short	27
	.short	139
	.short	65535
	.short	65535
	.short	351
	.short	283
	.short	395
	.short	65535
	.short	65535
	.short	671
	.short	731
	.short	715
	.short	65535
	.short	65535
	.short	863
	.short	923
	.short	907
	.short	65535
	.short	65535
	.short	1119
	.short	1243
	.short	1227
	.short	65535
	.short	65535
	.short	1311
	.short	1307
	.short	1291
	.short	65535
	.short	65535
	.short	1567
	.short	1691
	.short	1739
	.short	65535
	.short	65535
	.short	1887
	.short	1883
	.short	1803
	.short	65535
	.short	65535
	.short	223
	.short	155
	.short	203
	.short	65535
	.short	65535
	.short	479
	.short	475
	.short	331
	.short	65535
	.short	65535
	.short	543
	.short	539
	.short	651
	.short	65535
	.short	65535
	.short	927
	.short	859
	.short	843
	.short	65535
	.short	65535
	.short	1183
	.short	1115
	.short	1099
	.short	65535
	.short	65535
	.short	1439
	.short	1435
	.short	1419
	.short	65535
	.short	65535
	.short	1631
	.short	1755
	.short	1675
	.short	65535
	.short	65535
	.short	1951
	.short	1947
	.short	1995
	.short	65535
	.short	65535
	.short	26
	.short	144
	.short	73
	.short	196
	.short	65535
	.short	282
	.short	464
	.short	393
	.short	452
	.short	65535
	.short	666
	.short	528
	.short	713
	.short	580
	.short	65535
	.short	986
	.short	784
	.short	777
	.short	772
	.short	65535
	.short	1242
	.short	1104
	.short	1225
	.short	1156
	.short	65535
	.short	1498
	.short	1424
	.short	1353
	.short	1476
	.short	65535
	.short	1562
	.short	1744
	.short	1737
	.short	1668
	.short	65535
	.short	1818
	.short	1936
	.short	1993
	.short	1924
	.short	65535
	.short	154
	.short	16
	.short	137
	.short	68
	.short	65535
	.short	474
	.short	272
	.short	265
	.short	388
	.short	65535
	.short	538
	.short	720
	.short	649
	.short	644
	.short	65535
	.short	794
	.short	976
	.short	905
	.short	900
	.short	65535
	.short	1050
	.short	1232
	.short	1161
	.short	1092
	.short	65535
	.short	1434
	.short	1296
	.short	1417
	.short	1348
	.short	65535
	.short	1690
	.short	1680
	.short	1545
	.short	1540
	.short	65535
	.short	1882
	.short	2000
	.short	1801
	.short	1796
	.short	65535
	.size	_ZL7idx_tab, 2560

	.type	__hip_cuid_794236f6d9ab0dff,@object
